# final-norm exchange: the partner granules of a row requested together (two 16-byte loads) instead of slot by slot
# baseline (speedup 1.0000x reference)
; #define PG8_LAS __attribute__((address_space(3)))
;     __device__ __forceinline__ void fused(f32x4 (&acc)[2][2][4][2], const Unit& u, int wr, int wc, int fr, int fq, PG8_LAS unsigned char* lds, int wid, int lane) const {
;     ...
;         if (tid < 256) { const f32x4 p = *(const PG8_LAS f32x4*)(Pp + tid * 4); const float mine = (p[0] + p[1]) + (p[2] + p[3]);
;             unsigned long long* sl = slots + (size_t)(u.pm * BM + tid) * 4;
;             __hip_atomic_store(sl + u.pn, (1ull << 32) | (unsigned long long)__float_as_uint(mine), __ATOMIC_RELAXED, __HIP_MEMORY_SCOPE_AGENT);
.LBB0_832:
	s_or_b64 exec, exec, s[0:1]
	s_waitcnt lgkmcnt(0)
	s_barrier
	s_andn2_b32 s5, s5, 63
	s_waitcnt lgkmcnt(0)
	v_or_b32_e32 v1, s5, v232
	s_movk_i32 s0, 0x100
	v_cmp_gt_i32_e32 vcc, s0, v1
	s_and_saveexec_b64 s[2:3], vcc
	s_cbranch_execz .LBB0_858
	v_lshl_add_u32 v0, v1, 4, 0
	ds_read_b128 v[2:5], v0
	v_add_u32_e32 v6, s12, v1
	v_ashrrev_i32_e32 v7, 31, v6
	s_mov_b64 s[0:1], 0x1700000
	s_ashr_i32 s5, s4, 31
	s_waitcnt lgkmcnt(0)
	v_mov_b32_e32 v8, v3
	v_mov_b32_e32 v9, v4
	v_mov_b32_e32 v3, v5
	v_lshlrev_b64 v[4:5], 5, v[6:7]
	v_lshl_add_u64 v[4:5], s[54:55], 0, v[4:5]
	v_pk_add_f32 v[2:3], v[8:9], v[2:3]
	v_lshl_add_u64 v[4:5], v[4:5], 0, s[0:1]
	v_add_f32_e32 v2, v2, v3
	v_lshl_add_u64 v[6:7], s[4:5], 3, v[4:5]
	v_mov_b32_e32 v3, 1
	s_mov_b32 s6, 0
	global_store_dwordx2 v[6:7], v[2:3], off sc1
	s_mov_b32 s6, 0

;     __device__ __forceinline__ void fused(f32x4 (&acc)[2][2][4][2], const Unit& u, int wr, int wc, int fr, int fq, PG8_LAS unsigned char* lds, int wid, int lane) const {
;     ...
;             float tot = 0.f;
; #pragma unroll
;             for (int t = 0; t < 4; ++t) { float val = mine;
;                 if (t != u.pn) { unsigned long long v; unsigned sp = 0;
;                     for (;;) { v = __hip_atomic_load(sl + t, __ATOMIC_RELAXED, __HIP_MEMORY_SCOPE_AGENT); if ((unsigned)(v >> 32) == 1u || ++sp > (1u << 22)) break; __builtin_amdgcn_s_sleep(1); }
;                     val = __uint_as_float((unsigned)v); }
;                 tot += val; }
.Lp7_own3:
	v_and_b32_e32 v14, v7, v9
	v_and_b32_e32 v14, v14, v11
	v_and_b32_e32 v14, v14, v13
	v_cmp_ne_u32_e32 vcc, 1, v14
	s_cbranch_vccz .Lp7_ready
	s_add_i32 s6, s6, 1
	s_cmp_gt_u32 s6, 0x40000
	s_cbranch_scc1 .Lp7_ready
	s_sleep 1
	s_branch .Lp7_poll
